# XCD-local tile order in P4a/P4b/P6 GEMM phases (swap nt and low mt bits of the tile index so the 8 n-tiles of an m-tile run on one XCD; A tile fetched into one L2 instead of eight)
# speedup vs baseline: 1.0164x; 1.0147x over previous
; #define GM_LOAD(kt_) { GM_LOAD1(kt_, 0) GM_LOAD1(kt_, 1) GM_LOAD1(kt_, 2) GM_LOAD1(kt_, 3) GM_LOAD1(kt_, 4) GM_LOAD1(kt_, 5) GM_LOAD1(kt_, 6) GM_LOAD1(kt_, 7) }
; template <class AL>
; __device__ __forceinline__ void gemm_mainloop(f32x16 (&acc)[2][2], const AL& al, const u16* __restrict__ Bt, int ldb, int K, char* smem) {
;     ...
;   __syncthreads();
;   GM_LOAD(0)
;   GM_STORE(0, 0)
;   __syncthreads();
; __device__ __forceinline__ void phase4a(const Params& p, char* smem) {
;     ...
;     const int nt = it & 7, mt = it >> 3;
;     const int m0 = mt * 128, n0 = nt * 128;
;     unsigned sg[2][2][8];
;     f32x16 acc[2][2];
;     {
;       zero_acc(acc);
;       LoadBf16 lh{H + (size_t)m0 * 1024, 1024};
;       gemm_mainloop(acc, lh, WTIN + (size_t)(4096 + mix * 1024 + n0) * 1024, 1024, 1024, smem);
.LBB0_1128:
	s_lshr_b32 s65, s64, 3
	s_and_b32 s65, s65, 7
	s_and_b32 s0, s64, 7
	s_lshl_b32 s0, s0, 3
	s_or_b32 s65, s65, s0
	s_and_b32 s0, s64, 0xffffffc0
	s_or_b32 s65, s65, s0
	s_cmpk_lt_i32 s64, 0x400
	s_cselect_b32 s65, s65, s64
	s_lshl_b32 s0, s65, 4
	s_and_b32 s0, s0, 0xffffff80
	s_lshl_b32 s1, s65, 7
	s_and_b32 s65, s1, 0x380
	s_ashr_i32 s1, s0, 31
	s_xor_b64 s[18:19], s[16:17], -1
	s_and_b32 s66, s8, 1
	s_lshl_b64 s[20:21], s[0:1], 10
	s_lshl_b64 s[22:23], s[0:1], 11
	s_add_u32 s24, s38, s22
	s_addc_u32 s25, s39, s23
	s_lshl_b32 s8, s66, 21
	s_lshl_b32 s26, s65, 11
	s_or_b32 s8, s26, s8
	s_add_u32 s26, s80, s8
	s_addc_u32 s27, s81, 0
	s_waitcnt lgkmcnt(0)
	v_accvgpr_read_b32 v2, a104
	v_accvgpr_read_b32 v6, a106
	v_accvgpr_read_b32 v10, a108
	v_accvgpr_read_b32 v14, a110
	v_accvgpr_read_b32 v18, a112
	v_accvgpr_read_b32 v22, a114
	v_accvgpr_read_b32 v26, a116
	v_accvgpr_read_b32 v30, a118
	s_add_u32 s26, s26, 0x800000
	v_accvgpr_read_b32 v3, a105
	v_accvgpr_read_b32 v7, a107
	v_accvgpr_read_b32 v11, a109
	v_accvgpr_read_b32 v15, a111
	v_accvgpr_read_b32 v19, a113
	v_accvgpr_read_b32 v23, a115
	v_accvgpr_read_b32 v27, a117
	v_accvgpr_read_b32 v31, a119
	s_addc_u32 s27, s27, 0
	v_lshl_add_u64 v[0:1], s[24:25], 0, v[2:3]
	v_lshl_add_u64 v[4:5], s[24:25], 0, v[6:7]
	v_lshl_add_u64 v[8:9], s[24:25], 0, v[10:11]
	v_lshl_add_u64 v[12:13], s[24:25], 0, v[14:15]
	v_lshl_add_u64 v[16:17], s[24:25], 0, v[18:19]
	v_lshl_add_u64 v[20:21], s[24:25], 0, v[22:23]
	v_lshl_add_u64 v[24:25], s[24:25], 0, v[26:27]
	v_lshl_add_u64 v[28:29], s[24:25], 0, v[30:31]
	v_lshl_add_u64 v[32:33], v[0:1], 0, v[76:77]
	v_lshl_add_u64 v[0:1], s[26:27], 0, v[2:3]
	v_lshl_add_u64 v[36:37], v[4:5], 0, v[76:77]
	v_lshl_add_u64 v[4:5], s[26:27], 0, v[6:7]
	v_lshl_add_u64 v[38:39], v[8:9], 0, v[76:77]
	v_lshl_add_u64 v[8:9], s[26:27], 0, v[10:11]
	v_lshl_add_u64 v[40:41], v[12:13], 0, v[76:77]
	v_lshl_add_u64 v[12:13], s[26:27], 0, v[14:15]
	v_lshl_add_u64 v[42:43], v[16:17], 0, v[76:77]
	v_lshl_add_u64 v[16:17], s[26:27], 0, v[18:19]
	v_lshl_add_u64 v[44:45], v[20:21], 0, v[76:77]
	v_lshl_add_u64 v[20:21], s[26:27], 0, v[22:23]
	v_lshl_add_u64 v[46:47], v[24:25], 0, v[76:77]
	v_lshl_add_u64 v[24:25], s[26:27], 0, v[26:27]
	v_lshl_add_u64 v[48:49], v[28:29], 0, v[76:77]
	v_lshl_add_u64 v[28:29], s[26:27], 0, v[30:31]
	v_lshl_add_u64 v[0:1], v[0:1], 0, v[76:77]
	v_lshl_add_u64 v[4:5], v[4:5], 0, v[76:77]
	v_lshl_add_u64 v[8:9], v[8:9], 0, v[76:77]
	v_lshl_add_u64 v[12:13], v[12:13], 0, v[76:77]
	v_lshl_add_u64 v[16:17], v[16:17], 0, v[76:77]
	v_lshl_add_u64 v[20:21], v[20:21], 0, v[76:77]
	v_lshl_add_u64 v[24:25], v[24:25], 0, v[76:77]
	v_lshl_add_u64 v[28:29], v[28:29], 0, v[76:77]
	s_barrier
	global_load_dwordx4 v[0:3], v[0:1], off
	v_accvgpr_read_b32 v109, a103
	global_load_dwordx4 v[4:7], v[4:5], off
	v_accvgpr_write_b32 a15, 0
	global_load_dwordx4 v[8:11], v[8:9], off
	v_accvgpr_write_b32 a14, 0
	global_load_dwordx4 v[12:15], v[12:13], off
	v_accvgpr_write_b32 a13, 0
	global_load_dwordx4 v[16:19], v[16:17], off
	v_accvgpr_write_b32 a12, 0
	global_load_dwordx4 v[20:23], v[20:21], off
	v_accvgpr_write_b32 a11, 0
	global_load_dwordx4 v[24:27], v[24:25], off
	s_nop 0
	global_load_dwordx4 v[28:31], v[28:29], off
	s_nop 0
	global_load_dwordx4 v[32:35], v[32:33], off
	global_load_dwordx4 a[196:199], v[36:37], off
	global_load_dwordx4 a[200:203], v[38:39], off
	global_load_dwordx4 a[204:207], v[40:41], off
	global_load_dwordx4 a[208:211], v[42:43], off
	global_load_dwordx4 a[212:215], v[44:45], off
	global_load_dwordx4 a[216:219], v[46:47], off
	global_load_dwordx4 a[220:223], v[48:49], off
	v_accvgpr_write_b32 a10, 0
	v_accvgpr_write_b32 a9, 0
	v_accvgpr_write_b32 a8, 0
	v_accvgpr_write_b32 a7, 0
	v_accvgpr_write_b32 a6, 0
	v_accvgpr_write_b32 a5, 0
	v_accvgpr_write_b32 a4, 0
	v_accvgpr_write_b32 a3, 0
	v_accvgpr_write_b32 a2, 0
	v_accvgpr_write_b32 a1, 0
	s_waitcnt vmcnt(0)
	ds_write_b128 v134, v[32:35]
	ds_write_b128 v136, v[0:3]
	v_accvgpr_write_b32 a0, 0
	v_accvgpr_write_b32 a47, 0
	v_accvgpr_write_b32 a46, 0
	v_accvgpr_write_b32 a45, 0
	v_accvgpr_write_b32 a44, 0
	v_accvgpr_write_b32 a43, 0
	v_accvgpr_write_b32 a42, 0
	v_accvgpr_write_b32 a41, 0
	v_accvgpr_write_b32 a40, 0
	v_accvgpr_write_b32 a39, 0
	ds_write_b128 v134, a[196:199] offset:4352
	ds_write_b128 v138, v[4:7]
	v_accvgpr_write_b32 a38, 0
	v_accvgpr_write_b32 a37, 0
	v_accvgpr_write_b32 a36, 0
	v_accvgpr_write_b32 a35, 0
	v_accvgpr_write_b32 a34, 0
	v_accvgpr_write_b32 a33, 0
	v_accvgpr_write_b32 a32, 0
	v_accvgpr_write_b32 a63, 0
	v_accvgpr_write_b32 a62, 0
	v_accvgpr_write_b32 a61, 0
	ds_write_b128 v134, a[200:203] offset:8704
	ds_write_b128 v139, v[8:11]
	v_accvgpr_write_b32 a60, 0
	v_accvgpr_write_b32 a59, 0
	v_accvgpr_write_b32 a58, 0
	v_accvgpr_write_b32 a57, 0
	v_accvgpr_write_b32 a56, 0
	v_accvgpr_write_b32 a55, 0
	v_accvgpr_write_b32 a54, 0
	v_accvgpr_write_b32 a53, 0
	v_accvgpr_write_b32 a52, 0
	v_accvgpr_write_b32 a51, 0
	ds_write_b128 v134, a[204:207] offset:13056
	ds_write_b128 v176, v[12:15]
	v_accvgpr_write_b32 a50, 0
	v_accvgpr_write_b32 a49, 0
	v_accvgpr_write_b32 a48, 0
	v_accvgpr_write_b32 a31, 0
	v_accvgpr_write_b32 a30, 0
	v_accvgpr_write_b32 a29, 0
	v_accvgpr_write_b32 a28, 0
	v_accvgpr_write_b32 a27, 0
	v_accvgpr_write_b32 a26, 0
	v_accvgpr_write_b32 a25, 0
	ds_write_b128 v134, a[208:211] offset:17408
	ds_write_b128 v177, v[16:19]
	v_accvgpr_write_b32 a24, 0
	v_accvgpr_write_b32 a23, 0
	v_accvgpr_write_b32 a22, 0
	v_accvgpr_write_b32 a21, 0
	v_accvgpr_write_b32 a20, 0
	v_accvgpr_write_b32 a19, 0
	v_accvgpr_write_b32 a18, 0
	v_accvgpr_write_b32 a17, 0
	v_accvgpr_write_b32 a16, 0
	s_mov_b32 s67, 0
	ds_write_b128 v134, a[212:215] offset:21760
	ds_write_b128 v198, v[20:23]
	v_accvgpr_read_b32 v108, a102
	ds_write_b128 v134, a[216:219] offset:26112
	ds_write_b128 v200, v[24:27]
	ds_write_b128 v134, a[220:223] offset:30464
	ds_write_b128 v201, v[28:31]
	s_waitcnt lgkmcnt(0)
	s_barrier
	s_branch .LBB0_1130

; #define GM_LOAD(kt_) { GM_LOAD1(kt_, 0) GM_LOAD1(kt_, 1) GM_LOAD1(kt_, 2) GM_LOAD1(kt_, 3) GM_LOAD1(kt_, 4) GM_LOAD1(kt_, 5) GM_LOAD1(kt_, 6) GM_LOAD1(kt_, 7) }
; template <class AL>
; __device__ __forceinline__ void gemm_mainloop(f32x16 (&acc)[2][2], const AL& al, const u16* __restrict__ Bt, int ldb, int K, char* smem) {
;     ...
;   __syncthreads();
;   GM_LOAD(0)
;   GM_STORE(0, 0)
;   __syncthreads();
; __device__ __forceinline__ void phase4b(const Params& p, char* smem) {
;     ...
;   for (int it = blockIdx.x; it < 132 * 8; it += gridDim.x) {
;     const int nt = it & 7, mt = it >> 3;
;     const int m0 = mt * 128, n0 = nt * 128;
;     f32x16 acc[2][2]; zero_acc(acc);
;     LoadBf16 al{MRG + (size_t)m0 * 1024, 1024};
;     gemm_mainloop(acc, al, (const u16*)(ws + OFF_WT_OUT) + (size_t)n0 * 1024, 1024, 1024, smem);
.LBB0_1291:
	s_lshr_b32 s45, s44, 3
	s_and_b32 s45, s45, 7
	s_and_b32 s6, s44, 7
	s_lshl_b32 s6, s6, 3
	s_or_b32 s45, s45, s6
	s_and_b32 s6, s44, 0xffffffc0
	s_or_b32 s45, s45, s6
	s_cmpk_lt_i32 s44, 0x400
	s_cselect_b32 s45, s45, s44
	s_lshl_b32 s6, s45, 4
	s_and_b32 s6, s6, 0xffffff80
	s_ashr_i32 s7, s6, 31
	s_lshl_b64 s[8:9], s[6:7], 11
	s_lshl_b32 s6, s45, 4
	s_and_b32 s6, s6, 0xffffff80
	s_lshl_b32 s7, s45, 7
	s_lshl_b32 s0, s45, 18
	s_and_b32 s45, s7, 0x380
	s_ashr_i32 s7, s6, 31
	s_and_b32 s0, s0, 0x1c0000
	s_lshl_b64 s[10:11], s[6:7], 11
	s_add_u32 s10, s33, s10
	s_addc_u32 s11, s54, s11
	s_lshl_b32 s7, s45, 11
	s_add_u32 s46, s12, s7
	s_addc_u32 s47, s13, 0
	v_lshl_add_u64 v[0:1], s[10:11], 0, v[74:75]
	v_lshl_add_u64 v[8:9], v[0:1], 0, v[76:77]
	v_lshl_add_u64 v[0:1], s[46:47], 0, v[74:75]
	v_lshl_add_u64 v[4:5], v[0:1], 0, v[76:77]
	v_lshl_add_u64 v[0:1], s[10:11], 0, v[78:79]
	v_lshl_add_u64 v[16:17], v[0:1], 0, v[76:77]
	v_lshl_add_u64 v[0:1], s[46:47], 0, v[78:79]
	v_lshl_add_u64 v[12:13], v[0:1], 0, v[76:77]
	v_lshl_add_u64 v[0:1], s[10:11], 0, v[80:81]
	v_lshl_add_u64 v[24:25], v[0:1], 0, v[76:77]
	v_lshl_add_u64 v[0:1], s[46:47], 0, v[80:81]
	v_lshl_add_u64 v[20:21], v[0:1], 0, v[76:77]
	v_lshl_add_u64 v[0:1], s[10:11], 0, v[82:83]
	v_lshl_add_u64 v[32:33], v[0:1], 0, v[76:77]
	v_lshl_add_u64 v[0:1], s[46:47], 0, v[82:83]
	v_lshl_add_u64 v[28:29], v[0:1], 0, v[76:77]
	v_lshl_add_u64 v[0:1], s[10:11], 0, v[84:85]
	v_lshl_add_u64 v[40:41], v[0:1], 0, v[76:77]
	v_lshl_add_u64 v[0:1], s[46:47], 0, v[84:85]
	v_lshl_add_u64 v[36:37], v[0:1], 0, v[76:77]
	v_lshl_add_u64 v[0:1], s[10:11], 0, v[86:87]
	v_lshl_add_u64 v[48:49], v[0:1], 0, v[76:77]
	v_lshl_add_u64 v[0:1], s[46:47], 0, v[86:87]
	v_lshl_add_u64 v[44:45], v[0:1], 0, v[76:77]
	v_lshl_add_u64 v[0:1], s[10:11], 0, v[88:89]
	v_lshl_add_u64 v[56:57], v[0:1], 0, v[76:77]
	v_lshl_add_u64 v[0:1], s[46:47], 0, v[88:89]
	v_lshl_add_u64 v[52:53], v[0:1], 0, v[76:77]
	v_lshl_add_u64 v[0:1], s[10:11], 0, v[90:91]
	v_lshl_add_u64 v[0:1], v[0:1], 0, v[76:77]
	s_barrier
	global_load_dwordx4 v[0:3], v[0:1], off
	s_nop 0
	global_load_dwordx4 v[4:7], v[4:5], off
	s_nop 0
	global_load_dwordx4 v[8:11], v[8:9], off
	s_nop 0
	global_load_dwordx4 v[12:15], v[12:13], off
	s_nop 0
	global_load_dwordx4 v[16:19], v[16:17], off
	s_nop 0
	global_load_dwordx4 v[20:23], v[20:21], off
	s_nop 0
	global_load_dwordx4 v[24:27], v[24:25], off
	s_nop 0
	global_load_dwordx4 v[28:31], v[28:29], off
	s_nop 0
	global_load_dwordx4 v[32:35], v[32:33], off
	s_nop 0
	global_load_dwordx4 v[36:39], v[36:37], off
	s_nop 0
	global_load_dwordx4 v[40:43], v[40:41], off
	s_nop 0
	global_load_dwordx4 v[44:47], v[44:45], off
	s_nop 0
	global_load_dwordx4 v[48:51], v[48:49], off
	s_nop 0
	global_load_dwordx4 v[52:55], v[52:53], off
	s_nop 0
	global_load_dwordx4 v[56:59], v[56:57], off
	v_lshl_add_u64 v[60:61], s[46:47], 0, v[90:91]
	v_lshl_add_u64 v[60:61], v[60:61], 0, v[76:77]
	global_load_dwordx4 v[60:63], v[60:61], off
	s_mov_b32 s7, 0
	v_accvgpr_write_b32 a0, 0
	v_accvgpr_mov_b32 a1, a123
	v_lshl_add_u64 v[92:93], v[72:73], 0, s[0:1]
	v_lshl_add_u64 v[94:95], v[72:73], 0, s[8:9]
	v_accvgpr_mov_b32 a2, a122
	v_accvgpr_mov_b32 a3, a121
	v_accvgpr_mov_b32 a4, a120
	v_accvgpr_mov_b32 a5, a119
	v_accvgpr_mov_b32 a6, a118
	v_accvgpr_mov_b32 a7, a117
	v_accvgpr_mov_b32 a8, a116
	v_accvgpr_mov_b32 a9, a115
	v_accvgpr_mov_b32 a10, a114
	v_accvgpr_mov_b32 a11, a113
	v_accvgpr_mov_b32 a12, a112
	v_accvgpr_mov_b32 a13, a111
	v_accvgpr_mov_b32 a14, a110
	v_accvgpr_mov_b32 a15, a109
	v_accvgpr_write_b32 a16, 0
	v_accvgpr_mov_b32 a17, a108
	v_accvgpr_mov_b32 a18, a107
	v_accvgpr_mov_b32 a19, a106
	v_accvgpr_mov_b32 a20, a105
	v_accvgpr_mov_b32 a21, a104
	v_accvgpr_mov_b32 a22, a103
	v_accvgpr_mov_b32 a23, a102
	v_accvgpr_mov_b32 a24, a101
	v_accvgpr_mov_b32 a25, a100
	v_accvgpr_mov_b32 a26, a99
	v_accvgpr_mov_b32 a27, a98
	v_accvgpr_mov_b32 a28, a97
	v_accvgpr_mov_b32 a29, a96
	v_accvgpr_mov_b32 a30, a95
	v_accvgpr_mov_b32 a31, a94
	v_accvgpr_write_b32 a32, 0
	v_accvgpr_mov_b32 a33, a93
	v_accvgpr_mov_b32 a34, a92
	v_accvgpr_mov_b32 a35, a91
	v_accvgpr_mov_b32 a36, a90
	v_accvgpr_mov_b32 a37, a89
	v_accvgpr_mov_b32 a38, a88
	v_accvgpr_mov_b32 a39, a87
	v_accvgpr_mov_b32 a40, a86
	v_accvgpr_mov_b32 a41, a85
	v_accvgpr_mov_b32 a42, a84
	v_accvgpr_mov_b32 a43, a83
	v_accvgpr_mov_b32 a44, a82
	v_accvgpr_mov_b32 a45, a81
	v_accvgpr_mov_b32 a46, a80
	v_accvgpr_mov_b32 a47, a79
	v_accvgpr_write_b32 a48, 0
	v_accvgpr_mov_b32 a49, a78
	v_accvgpr_mov_b32 a50, a77
	v_accvgpr_mov_b32 a51, a76
	v_accvgpr_mov_b32 a52, a75
	v_accvgpr_mov_b32 a53, a74
	v_accvgpr_mov_b32 a54, a73
	v_accvgpr_mov_b32 a55, a72
	v_accvgpr_mov_b32 a56, a71
	v_accvgpr_mov_b32 a57, a70
	v_accvgpr_mov_b32 a58, a69
	v_accvgpr_mov_b32 a59, a68
	v_accvgpr_mov_b32 a60, a67
	v_accvgpr_mov_b32 a61, a66
	v_accvgpr_mov_b32 a62, a65
	v_accvgpr_mov_b32 a63, a64
	s_waitcnt vmcnt(15)
	ds_write_b128 v96, v[0:3] offset:30464
	s_waitcnt vmcnt(13)
	ds_write_b128 v96, v[8:11]
	ds_write_b128 v97, v[4:7]
	s_waitcnt vmcnt(11)
	ds_write_b128 v96, v[16:19] offset:4352
	ds_write_b128 v98, v[12:15]
	s_waitcnt vmcnt(9)
	ds_write_b128 v96, v[24:27] offset:8704
	ds_write_b128 v99, v[20:23]
	s_waitcnt vmcnt(7)
	ds_write_b128 v96, v[32:35] offset:13056
	ds_write_b128 v100, v[28:31]
	s_waitcnt vmcnt(5)
	ds_write_b128 v96, v[40:43] offset:17408
	ds_write_b128 v101, v[36:39]
	s_waitcnt vmcnt(3)
	ds_write_b128 v96, v[48:51] offset:21760
	ds_write_b128 v102, v[44:47]
	s_waitcnt vmcnt(1)
	ds_write_b128 v96, v[56:59] offset:26112
	ds_write_b128 v103, v[52:55]
	s_waitcnt vmcnt(0)
	ds_write_b128 v104, v[60:63]
	s_waitcnt lgkmcnt(0)
	s_barrier
	s_branch .LBB0_1293

; __device__ __forceinline__ void phase6(const Params& p, char* smem) {
;     ...
;   for (int it = blockIdx.x; it < 132 * 8; it += gridDim.x) {
;     const int nt = it & 7, mt = it >> 3;
;     const int m0 = mt * 128, n0 = nt * 128;
;     f32x16 acc1[2][2]; zero_acc(acc1);
;     unsigned pe[2][2][8];
;     {
;       LoadF32 lp{m0 < NTP ? p.p_prompt + (size_t)m0 * 256 : p.p_sample + (size_t)(m0 - NTP) * 256, 256};
.LBB0_1578:
	s_lshr_b32 s38, s37, 3
	s_and_b32 s38, s38, 7
	s_and_b32 s0, s37, 7
	s_lshl_b32 s0, s0, 3
	s_or_b32 s38, s38, s0
	s_and_b32 s0, s37, 0xffffffc0
	s_or_b32 s38, s38, s0
	s_cmpk_lt_i32 s37, 0x400
	s_cselect_b32 s38, s38, s37
	s_lshl_b32 s0, s38, 4
	s_and_b32 s8, s0, 0xffffff80
	s_cmpk_gt_i32 s8, 0x3fff
	s_mov_b64 s[12:13], -1
	s_cbranch_scc0 .LBB0_1580
	s_add_i32 s0, s8, 0xffffc000
	s_lshl_b64 s[10:11], s[0:1], 10
	s_add_u32 s10, s52, s10
	s_addc_u32 s11, s53, s11
	s_mov_b32 s9, s1
	s_mov_b64 s[12:13], 0

; __device__ __forceinline__ void phase6(const Params& p, char* smem) {
;     ...
;       LoadF32 lp{m0 < NTP ? p.p_prompt + (size_t)m0 * 256 : p.p_sample + (size_t)(m0 - NTP) * 256, 256};
;       gemm_mainloop(acc1, lp, (const u16*)(ws + OFF_WT_PLE) + (size_t)n0 * 256, 256, 256, smem);
.LBB0_1582:
	s_lshl_b32 s12, s38, 7
	s_lshl_b32 s0, s38, 18
	s_and_b32 s38, s12, 0x380
	s_and_b32 s0, s0, 0x1c0000
	s_lshl_b32 s12, s38, 9
	s_add_u32 s12, s14, s12
	v_accvgpr_read_b32 v0, a68
	s_addc_u32 s13, s15, 0
	v_accvgpr_read_b32 v1, a69
	v_lshl_add_u64 v[0:1], s[10:11], 0, v[0:1]
	v_lshl_add_u64 v[8:9], s[12:13], 0, v[168:169]
	v_lshl_add_u64 v[12:13], s[10:11], 0, v[128:129]
	v_lshl_add_u64 v[96:97], v[0:1], 0, v[166:167]
	v_lshl_add_u64 v[98:99], v[8:9], 0, v[170:171]
	v_lshl_add_u64 v[100:101], v[12:13], 0, v[166:167]
	v_lshl_add_u64 v[20:21], s[12:13], 0, v[172:173]
	v_lshl_add_u64 v[24:25], s[10:11], 0, v[160:161]
	v_lshl_add_u64 v[32:33], s[10:11], 0, v[136:137]
	v_lshl_add_u64 v[40:41], s[12:13], 0, v[174:175]
	v_lshl_add_u64 v[44:45], s[12:13], 0, v[180:181]
	v_lshl_add_u64 v[48:49], s[10:11], 0, v[138:139]
	s_barrier
	s_waitcnt lgkmcnt(0)
	global_load_dwordx4 v[0:3], v[96:97], off offset:16
	global_load_dwordx4 v[4:7], v[96:97], off
	global_load_dwordx4 v[8:11], v[98:99], off
	global_load_dwordx4 v[12:15], v[100:101], off offset:16
	global_load_dwordx4 v[16:19], v[100:101], off
	v_lshl_add_u64 v[102:103], v[20:21], 0, v[170:171]
	v_lshl_add_u64 v[104:105], v[24:25], 0, v[166:167]
	v_lshl_add_u64 v[106:107], v[32:33], 0, v[166:167]
	v_lshl_add_u64 v[108:109], v[40:41], 0, v[170:171]
	v_lshl_add_u64 v[110:111], v[44:45], 0, v[170:171]
	v_lshl_add_u64 v[112:113], v[48:49], 0, v[166:167]
	v_lshl_add_u64 v[56:57], s[12:13], 0, v[182:183]
	v_lshl_add_u64 v[60:61], s[10:11], 0, v[140:141]
	global_load_dwordx4 v[20:23], v[102:103], off
	global_load_dwordx4 v[24:27], v[104:105], off offset:16
	global_load_dwordx4 v[28:31], v[104:105], off
	global_load_dwordx4 v[32:35], v[106:107], off offset:16
	global_load_dwordx4 v[36:39], v[106:107], off
	global_load_dwordx4 v[40:43], v[108:109], off
	global_load_dwordx4 v[44:47], v[110:111], off
	global_load_dwordx4 v[48:51], v[112:113], off offset:16
	global_load_dwordx4 v[52:55], v[112:113], off
	v_lshl_add_u64 v[114:115], v[56:57], 0, v[170:171]
	v_lshl_add_u64 v[116:117], v[60:61], 0, v[166:167]
	v_lshl_add_u64 v[68:69], s[12:13], 0, v[184:185]
	v_lshl_add_u64 v[72:73], s[10:11], 0, v[142:143]
	global_load_dwordx4 v[56:59], v[114:115], off
	global_load_dwordx4 v[60:63], v[116:117], off offset:16
	global_load_dwordx4 v[64:67], v[116:117], off
	v_lshl_add_u64 v[118:119], v[68:69], 0, v[170:171]
	v_lshl_add_u64 v[120:121], v[72:73], 0, v[166:167]
	v_lshl_add_u64 v[80:81], s[12:13], 0, v[186:187]
	v_lshl_add_u64 v[84:85], s[10:11], 0, v[144:145]
	global_load_dwordx4 v[68:71], v[118:119], off
	global_load_dwordx4 v[72:75], v[120:121], off offset:16
	global_load_dwordx4 v[76:79], v[120:121], off
	v_lshl_add_u64 v[122:123], v[80:81], 0, v[170:171]
	v_lshl_add_u64 v[124:125], v[84:85], 0, v[166:167]
	global_load_dwordx4 v[80:83], v[122:123], off
	global_load_dwordx4 v[84:87], v[124:125], off
	global_load_dwordx4 v[88:91], v[124:125], off offset:16
	v_lshl_add_u64 v[92:93], s[12:13], 0, v[188:189]
	v_lshl_add_u64 v[126:127], v[92:93], 0, v[170:171]
	global_load_dwordx4 v[92:95], v[126:127], off
	v_accvgpr_write_b32 a84, v135
	v_lshl_add_u64 v[206:207], v[164:165], 0, s[0:1]
	s_waitcnt vmcnt(22)
	v_cvt_pk_bf16_f32 v4, v4, v5
	v_cvt_pk_bf16_f32 v5, v6, v7
	v_cvt_pk_bf16_f32 v6, v0, v1
	v_cvt_pk_bf16_f32 v7, v2, v3
	s_waitcnt vmcnt(19)
	v_cvt_pk_bf16_f32 v0, v16, v17
	v_cvt_pk_bf16_f32 v1, v18, v19
	v_cvt_pk_bf16_f32 v2, v12, v13
	v_cvt_pk_bf16_f32 v3, v14, v15
	s_waitcnt vmcnt(17)
	v_cvt_pk_bf16_f32 v14, v24, v25
	s_waitcnt vmcnt(16)
	v_cvt_pk_bf16_f32 v12, v28, v29
	v_cvt_pk_bf16_f32 v13, v30, v31
	v_cvt_pk_bf16_f32 v15, v26, v27
	s_waitcnt vmcnt(14)
	v_cvt_pk_bf16_f32 v16, v36, v37
	v_cvt_pk_bf16_f32 v17, v38, v39
	v_cvt_pk_bf16_f32 v18, v32, v33
	v_cvt_pk_bf16_f32 v19, v34, v35
	ds_write_b128 v176, v[4:7]
	ds_write_b128 v176, v[0:3] offset:4352
	ds_write_b128 v176, v[12:15] offset:8704
	ds_write_b128 v177, v[8:11]
	ds_write_b128 v178, v[20:23]
	s_waitcnt vmcnt(13)
	ds_write_b128 v179, v[40:43]
	ds_write_b128 v176, v[16:19] offset:13056
	s_waitcnt vmcnt(12)
	ds_write_b128 v210, v[44:47]
	s_waitcnt vmcnt(10)
	v_cvt_pk_bf16_f32 v0, v52, v53
	v_cvt_pk_bf16_f32 v1, v54, v55
	v_cvt_pk_bf16_f32 v2, v48, v49
	v_cvt_pk_bf16_f32 v3, v50, v51
	ds_write_b128 v176, v[0:3] offset:17408
	s_waitcnt vmcnt(9)
	ds_write_b128 v211, v[56:59]
	s_waitcnt vmcnt(7)
	v_cvt_pk_bf16_f32 v0, v64, v65
	v_cvt_pk_bf16_f32 v1, v66, v67
	v_cvt_pk_bf16_f32 v2, v60, v61
	v_cvt_pk_bf16_f32 v3, v62, v63
	ds_write_b128 v176, v[0:3] offset:21760
	s_waitcnt vmcnt(6)
	ds_write_b128 v212, v[68:71]
	s_waitcnt vmcnt(4)
	v_cvt_pk_bf16_f32 v0, v76, v77
	v_cvt_pk_bf16_f32 v1, v78, v79
	v_cvt_pk_bf16_f32 v2, v72, v73
	v_cvt_pk_bf16_f32 v3, v74, v75
	ds_write_b128 v176, v[0:3] offset:26112
	s_waitcnt vmcnt(3)
	ds_write_b128 v213, v[80:83]
	s_waitcnt vmcnt(2)
	v_cvt_pk_bf16_f32 v0, v84, v85
	v_cvt_pk_bf16_f32 v1, v86, v87
	s_waitcnt vmcnt(1)
	v_cvt_pk_bf16_f32 v2, v88, v89
	v_cvt_pk_bf16_f32 v3, v90, v91
	ds_write_b128 v176, v[0:3] offset:30464
	s_waitcnt vmcnt(0)
	ds_write_b128 v214, v[92:95]
	s_waitcnt lgkmcnt(0)
	s_barrier
	global_load_dwordx4 v[0:3], v[98:99], off offset:256
	global_load_dwordx4 v[4:7], v[102:103], off offset:256
	global_load_dwordx4 v[8:11], v[108:109], off offset:256
	global_load_dwordx4 v[12:15], v[110:111], off offset:256
	global_load_dwordx4 v[16:19], v[114:115], off offset:256
	global_load_dwordx4 v[20:23], v[118:119], off offset:256
	global_load_dwordx4 v[24:27], v[122:123], off offset:256
	global_load_dwordx4 v[28:31], v[126:127], off offset:256
	global_load_dwordx4 v[32:35], v[96:97], off offset:528
	global_load_dwordx4 v[36:39], v[96:97], off offset:512
	global_load_dwordx4 v[40:43], v[100:101], off offset:528
	global_load_dwordx4 v[44:47], v[100:101], off offset:512
	global_load_dwordx4 v[48:51], v[104:105], off offset:528
	global_load_dwordx4 v[52:55], v[104:105], off offset:512
	global_load_dwordx4 v[56:59], v[106:107], off offset:528
	global_load_dwordx4 v[60:63], v[106:107], off offset:512
	global_load_dwordx4 v[64:67], v[112:113], off offset:528
	global_load_dwordx4 v[68:71], v[112:113], off offset:512
	global_load_dwordx4 v[72:75], v[116:117], off offset:528
	global_load_dwordx4 v[76:79], v[116:117], off offset:512
	global_load_dwordx4 v[80:83], v[120:121], off offset:528
	global_load_dwordx4 v[84:87], v[120:121], off offset:512
	global_load_dwordx4 v[88:91], v[124:125], off offset:528
	global_load_dwordx4 v[92:95], v[124:125], off offset:512
	ds_read_b128 v[96:99], v218
	ds_read_b128 v[100:103], v219
	ds_read_b128 v[104:107], v216
	ds_read_b128 v[108:111], v216 offset:32
	ds_read_b128 v[112:115], v216 offset:8704
	ds_read_b128 v[116:119], v216 offset:8736
	ds_read_b128 v[120:123], v220 offset:32
	ds_read_b128 v[124:127], v220 offset:8736
	s_waitcnt lgkmcnt(5)
	v_mfma_f32_32x32x16_bf16 a[16:31], v[104:107], v[96:99], 0
	s_mov_b32 s0, 0
	v_mfma_f32_32x32x16_bf16 a[32:47], v[104:107], v[100:103], 0
	s_waitcnt lgkmcnt(3)
	v_mfma_f32_32x32x16_bf16 a[48:63], v[112:115], v[96:99], 0
	v_mfma_f32_32x32x16_bf16 a[0:15], v[112:115], v[100:103], 0
	ds_read_b128 v[96:99], v220 offset:8768
	ds_read_b128 v[100:103], v220 offset:64
	ds_read_b128 v[104:107], v216 offset:8768
	ds_read_b128 v[112:115], v216 offset:64
	s_waitcnt lgkmcnt(5)
	v_mfma_f32_32x32x16_bf16 a[16:31], v[108:111], v[120:123], a[16:31]
	s_waitcnt lgkmcnt(4)
	v_mfma_f32_32x32x16_bf16 a[32:47], v[108:111], v[124:127], a[32:47]
	v_mfma_f32_32x32x16_bf16 a[48:63], v[116:119], v[120:123], a[48:63]
	v_mfma_f32_32x32x16_bf16 a[0:15], v[116:119], v[124:127], a[0:15]
	ds_read_b128 v[108:111], v216 offset:96
	ds_read_b128 v[116:119], v216 offset:8800
	ds_read_b128 v[120:123], v220 offset:96
	ds_read_b128 v[124:127], v220 offset:8800
	s_waitcnt lgkmcnt(4)
	v_mfma_f32_32x32x16_bf16 a[16:31], v[112:115], v[100:103], a[16:31]
	v_mfma_f32_32x32x16_bf16 a[32:47], v[112:115], v[96:99], a[32:47]
	v_mfma_f32_32x32x16_bf16 a[48:63], v[104:107], v[100:103], a[48:63]
	v_mfma_f32_32x32x16_bf16 a[0:15], v[104:107], v[96:99], a[0:15]
	ds_read_b128 v[96:99], v220 offset:8832
	ds_read_b128 v[100:103], v220 offset:128
	ds_read_b128 v[104:107], v216 offset:8832
	ds_read_b128 v[112:115], v216 offset:128
	s_waitcnt lgkmcnt(5)
	v_mfma_f32_32x32x16_bf16 a[16:31], v[108:111], v[120:123], a[16:31]
	s_waitcnt lgkmcnt(4)
	v_mfma_f32_32x32x16_bf16 a[32:47], v[108:111], v[124:127], a[32:47]
	v_mfma_f32_32x32x16_bf16 a[48:63], v[116:119], v[120:123], a[48:63]
	v_mfma_f32_32x32x16_bf16 a[0:15], v[116:119], v[124:127], a[0:15]
	ds_read_b128 v[108:111], v216 offset:160
	ds_read_b128 v[116:119], v216 offset:8864
	ds_read_b128 v[120:123], v220 offset:160
	ds_read_b128 v[124:127], v220 offset:8864
	s_waitcnt lgkmcnt(4)
	v_mfma_f32_32x32x16_bf16 a[16:31], v[112:115], v[100:103], a[16:31]
	v_mfma_f32_32x32x16_bf16 a[32:47], v[112:115], v[96:99], a[32:47]
	v_mfma_f32_32x32x16_bf16 a[48:63], v[104:107], v[100:103], a[48:63]
	v_mfma_f32_32x32x16_bf16 a[0:15], v[104:107], v[96:99], a[0:15]
	ds_read_b128 v[96:99], v220 offset:8896
	ds_read_b128 v[100:103], v220 offset:192
	ds_read_b128 v[104:107], v216 offset:8896
	ds_read_b128 v[112:115], v216 offset:192
	s_waitcnt lgkmcnt(5)
	v_mfma_f32_32x32x16_bf16 a[16:31], v[108:111], v[120:123], a[16:31]
	s_waitcnt lgkmcnt(4)
	v_mfma_f32_32x32x16_bf16 a[32:47], v[108:111], v[124:127], a[32:47]
	v_mfma_f32_32x32x16_bf16 a[48:63], v[116:119], v[120:123], a[48:63]
	v_mfma_f32_32x32x16_bf16 a[0:15], v[116:119], v[124:127], a[0:15]
	ds_read_b128 v[108:111], v216 offset:224
	ds_read_b128 v[116:119], v216 offset:8928
	ds_read_b128 v[120:123], v220 offset:224
	ds_read_b128 v[124:127], v220 offset:8928
	s_waitcnt lgkmcnt(4)
	v_mfma_f32_32x32x16_bf16 a[16:31], v[112:115], v[100:103], a[16:31]
	v_mfma_f32_32x32x16_bf16 a[32:47], v[112:115], v[96:99], a[32:47]
	v_mfma_f32_32x32x16_bf16 a[48:63], v[104:107], v[100:103], a[48:63]
	v_mfma_f32_32x32x16_bf16 a[0:15], v[104:107], v[96:99], a[0:15]
	s_waitcnt lgkmcnt(1)
	v_mfma_f32_32x32x16_bf16 a[16:31], v[108:111], v[120:123], a[16:31]
	s_waitcnt lgkmcnt(0)
	v_mfma_f32_32x32x16_bf16 a[32:47], v[108:111], v[124:127], a[32:47]
	v_mfma_f32_32x32x16_bf16 a[48:63], v[116:119], v[120:123], a[48:63]
	v_mfma_f32_32x32x16_bf16 a[0:15], v[116:119], v[124:127], a[0:15]
	s_waitcnt vmcnt(14)
	v_cvt_pk_bf16_f32 v36, v36, v37
	v_cvt_pk_bf16_f32 v37, v38, v39
	v_cvt_pk_bf16_f32 v38, v32, v33
	v_cvt_pk_bf16_f32 v39, v34, v35
	ds_write_b128 v176, v[36:39] offset:34816
	ds_write_b128 v224, v[0:3]
	s_waitcnt vmcnt(12)
	v_cvt_pk_bf16_f32 v0, v44, v45
	v_cvt_pk_bf16_f32 v1, v46, v47
	v_cvt_pk_bf16_f32 v2, v40, v41
	v_cvt_pk_bf16_f32 v3, v42, v43
	ds_write_b128 v176, v[0:3] offset:39168
	ds_write_b128 v225, v[4:7]
	s_waitcnt vmcnt(10)
	v_cvt_pk_bf16_f32 v0, v52, v53
	v_cvt_pk_bf16_f32 v1, v54, v55
	v_cvt_pk_bf16_f32 v2, v48, v49
	v_cvt_pk_bf16_f32 v3, v50, v51
	ds_write_b128 v176, v[0:3] offset:43520
	ds_write_b128 v226, v[8:11]
	s_waitcnt vmcnt(8)
	v_cvt_pk_bf16_f32 v0, v60, v61
	v_cvt_pk_bf16_f32 v1, v62, v63
	v_cvt_pk_bf16_f32 v2, v56, v57
	v_cvt_pk_bf16_f32 v3, v58, v59
	ds_write_b128 v176, v[0:3] offset:47872
	ds_write_b128 v227, v[12:15]
	s_waitcnt vmcnt(6)
	v_cvt_pk_bf16_f32 v0, v68, v69
	v_cvt_pk_bf16_f32 v1, v70, v71
	v_cvt_pk_bf16_f32 v2, v64, v65
	v_cvt_pk_bf16_f32 v3, v66, v67
	ds_write_b128 v176, v[0:3] offset:52224
	ds_write_b128 v228, v[16:19]
	s_waitcnt vmcnt(4)
	v_cvt_pk_bf16_f32 v0, v76, v77
	v_cvt_pk_bf16_f32 v1, v78, v79
	v_cvt_pk_bf16_f32 v2, v72, v73
	v_cvt_pk_bf16_f32 v3, v74, v75
	ds_write_b128 v176, v[0:3] offset:56576
	ds_write_b128 v229, v[20:23]
	s_waitcnt vmcnt(2)
	v_cvt_pk_bf16_f32 v0, v84, v85
	v_cvt_pk_bf16_f32 v1, v86, v87
	v_cvt_pk_bf16_f32 v2, v80, v81
	v_cvt_pk_bf16_f32 v3, v82, v83
	ds_write_b128 v176, v[0:3] offset:60928
	ds_write_b128 v230, v[24:27]
	s_waitcnt vmcnt(0)
	v_cvt_pk_bf16_f32 v0, v92, v93
	v_cvt_pk_bf16_f32 v1, v94, v95
	v_cvt_pk_bf16_f32 v2, v88, v89
	v_cvt_pk_bf16_f32 v3, v90, v91
	ds_write_b128 v176, v[0:3] offset:65280
	ds_write_b128 v221, v[28:31]
	s_waitcnt lgkmcnt(0)
	s_barrier
; __device__ __forceinline__ void phase6(const Params& p, char* smem) {
;     ...
; #pragma unroll
;       for (int i = 0; i < 2; i++)
; #pragma unroll
;         for (int j = 0; j < 2; j++)
; #pragma unroll
;           for (int e = 0; e < 8; e++) pe[i][j][e] = pack2(acc1[i][j][2 * e], acc1[i][j][2 * e + 1]);
;       zero_acc(acc1);
;     }
;     LoadBf16 al{H3 + (size_t)m0 * 1024, 1024};
;     gemm_mainloop(acc1, al, (const u16*)(ws + OFF_WT_PG) + (size_t)n0 * 1024, 1024, 1024, smem);
	ds_read_b128 v[0:3], v216 offset:34816
	ds_read_b128 v[4:7], v216 offset:34848
	ds_read_b128 v[8:11], v216 offset:43520
	ds_read_b128 v[12:15], v216 offset:43552
	ds_read_b128 v[16:19], v222
	ds_read_b128 v[20:23], v223 offset:32
	ds_read_b128 v[24:27], v231
	ds_read_b128 v[28:31], v223 offset:8736
	s_waitcnt lgkmcnt(1)
	v_mfma_f32_32x32x16_bf16 a[16:31], v[0:3], v[24:27], a[16:31]
	v_mfma_f32_32x32x16_bf16 a[32:47], v[0:3], v[16:19], a[32:47]
	v_mfma_f32_32x32x16_bf16 a[48:63], v[8:11], v[24:27], a[48:63]
	v_mfma_f32_32x32x16_bf16 a[0:15], v[8:11], v[16:19], a[0:15]
	ds_read_b128 v[0:3], v223 offset:8768
	ds_read_b128 v[8:11], v223 offset:64
	ds_read_b128 v[16:19], v216 offset:43584
	ds_read_b128 v[24:27], v216 offset:34880
	v_mfma_f32_32x32x16_bf16 a[16:31], v[4:7], v[20:23], a[16:31]
	s_waitcnt lgkmcnt(4)
	v_mfma_f32_32x32x16_bf16 a[32:47], v[4:7], v[28:31], a[32:47]
	v_mfma_f32_32x32x16_bf16 a[48:63], v[12:15], v[20:23], a[48:63]
	v_mfma_f32_32x32x16_bf16 a[0:15], v[12:15], v[28:31], a[0:15]
	ds_read_b128 v[4:7], v216 offset:34912
	ds_read_b128 v[12:15], v216 offset:43616
	ds_read_b128 v[20:23], v223 offset:96
	ds_read_b128 v[28:31], v223 offset:8800
	s_waitcnt lgkmcnt(4)
	v_mfma_f32_32x32x16_bf16 a[16:31], v[24:27], v[8:11], a[16:31]
	v_mfma_f32_32x32x16_bf16 a[32:47], v[24:27], v[0:3], a[32:47]
	v_mfma_f32_32x32x16_bf16 a[48:63], v[16:19], v[8:11], a[48:63]
	v_mfma_f32_32x32x16_bf16 a[0:15], v[16:19], v[0:3], a[0:15]
	ds_read_b128 v[0:3], v223 offset:8832
	ds_read_b128 v[8:11], v223 offset:128
	ds_read_b128 v[16:19], v216 offset:43648
	ds_read_b128 v[24:27], v216 offset:34944
	s_waitcnt lgkmcnt(5)
	v_mfma_f32_32x32x16_bf16 a[16:31], v[4:7], v[20:23], a[16:31]
	s_waitcnt lgkmcnt(4)
	v_mfma_f32_32x32x16_bf16 a[32:47], v[4:7], v[28:31], a[32:47]
	v_mfma_f32_32x32x16_bf16 a[48:63], v[12:15], v[20:23], a[48:63]
	v_mfma_f32_32x32x16_bf16 a[0:15], v[12:15], v[28:31], a[0:15]
	ds_read_b128 v[4:7], v216 offset:34976
	ds_read_b128 v[12:15], v216 offset:43680
	ds_read_b128 v[20:23], v223 offset:160
	ds_read_b128 v[28:31], v223 offset:8864
	s_waitcnt lgkmcnt(4)
	v_mfma_f32_32x32x16_bf16 a[16:31], v[24:27], v[8:11], a[16:31]
	v_mfma_f32_32x32x16_bf16 a[32:47], v[24:27], v[0:3], a[32:47]
	v_mfma_f32_32x32x16_bf16 a[48:63], v[16:19], v[8:11], a[48:63]
	v_mfma_f32_32x32x16_bf16 a[0:15], v[16:19], v[0:3], a[0:15]
	ds_read_b128 v[0:3], v223 offset:8896
	ds_read_b128 v[8:11], v223 offset:192
	ds_read_b128 v[16:19], v216 offset:43712
	ds_read_b128 v[24:27], v216 offset:35008
	s_waitcnt lgkmcnt(5)
	v_mfma_f32_32x32x16_bf16 a[16:31], v[4:7], v[20:23], a[16:31]
	s_waitcnt lgkmcnt(4)
	v_mfma_f32_32x32x16_bf16 a[32:47], v[4:7], v[28:31], a[32:47]
	v_mfma_f32_32x32x16_bf16 a[48:63], v[12:15], v[20:23], a[48:63]
	v_mfma_f32_32x32x16_bf16 a[0:15], v[12:15], v[28:31], a[0:15]
	ds_read_b128 v[4:7], v216 offset:35040
	ds_read_b128 v[20:23], v216 offset:43744
	ds_read_b128 v[12:15], v223 offset:224
	ds_read_b128 v[28:31], v223 offset:8928
	s_waitcnt lgkmcnt(4)
	v_mfma_f32_32x32x16_bf16 a[16:31], v[24:27], v[8:11], a[16:31]
	v_mfma_f32_32x32x16_bf16 a[32:47], v[24:27], v[0:3], a[32:47]
	v_mfma_f32_32x32x16_bf16 a[48:63], v[16:19], v[8:11], a[48:63]
	v_mfma_f32_32x32x16_bf16 a[0:15], v[16:19], v[0:3], a[0:15]
	s_waitcnt lgkmcnt(1)
	v_mfma_f32_32x32x16_bf16 a[16:31], v[4:7], v[12:15], a[16:31]
	s_waitcnt lgkmcnt(0)
	v_mfma_f32_32x32x16_bf16 a[32:47], v[4:7], v[28:31], a[32:47]
	s_nop 9
	v_accvgpr_read_b32 v47, a31
	v_accvgpr_read_b32 v46, a30
	v_accvgpr_read_b32 v45, a29
	v_mfma_f32_32x32x16_bf16 a[48:63], v[20:23], v[12:15], a[48:63]
	v_accvgpr_read_b32 v44, a28
	v_accvgpr_read_b32 v43, a27
	v_accvgpr_read_b32 v42, a26
	v_accvgpr_read_b32 v41, a25
	v_accvgpr_read_b32 v63, a47
	v_accvgpr_read_b32 v40, a24
	v_accvgpr_read_b32 v39, a23
	v_mfma_f32_32x32x16_bf16 a[0:15], v[20:23], v[28:31], a[0:15]
	v_accvgpr_read_b32 v38, a22
	v_accvgpr_read_b32 v37, a21
	v_accvgpr_read_b32 v36, a20
	v_accvgpr_read_b32 v35, a19
	v_accvgpr_read_b32 v0, a48
	v_accvgpr_read_b32 v34, a18
	v_accvgpr_read_b32 v33, a17
	v_accvgpr_read_b32 v32, a16
	v_accvgpr_read_b32 v62, a46
	v_accvgpr_read_b32 v61, a45
	v_accvgpr_read_b32 v60, a44
	v_accvgpr_read_b32 v59, a43
	v_accvgpr_read_b32 v31, a15
	v_accvgpr_read_b32 v58, a42
	v_accvgpr_read_b32 v57, a41
	v_accvgpr_read_b32 v56, a40
	v_accvgpr_read_b32 v55, a39
	v_accvgpr_read_b32 v54, a38
	v_accvgpr_read_b32 v53, a37
	v_accvgpr_read_b32 v52, a36
	v_accvgpr_read_b32 v51, a35
	v_accvgpr_read_b32 v50, a34
	v_accvgpr_read_b32 v49, a33
	v_accvgpr_read_b32 v48, a32
	v_accvgpr_read_b32 v1, a49
	v_accvgpr_read_b32 v2, a50
	v_accvgpr_read_b32 v3, a51
	v_accvgpr_read_b32 v4, a52
	v_accvgpr_read_b32 v5, a53
	v_accvgpr_read_b32 v6, a54
	v_accvgpr_read_b32 v7, a55
	v_accvgpr_read_b32 v8, a56
	v_accvgpr_read_b32 v9, a57
	v_accvgpr_read_b32 v10, a58
	v_accvgpr_read_b32 v11, a59
	v_accvgpr_read_b32 v12, a60
	v_accvgpr_read_b32 v13, a61
	v_accvgpr_read_b32 v14, a62
	v_accvgpr_read_b32 v15, a63
	v_accvgpr_read_b32 v30, a14
	v_accvgpr_read_b32 v29, a13
	v_accvgpr_read_b32 v28, a12
	v_accvgpr_read_b32 v27, a11
	v_accvgpr_read_b32 v26, a10
	v_accvgpr_read_b32 v25, a9
	v_accvgpr_read_b32 v24, a8
	v_accvgpr_read_b32 v23, a7
	v_accvgpr_read_b32 v22, a6
	v_accvgpr_read_b32 v21, a5
	v_accvgpr_read_b32 v20, a4
	v_accvgpr_read_b32 v19, a3
	v_accvgpr_read_b32 v18, a2
	v_accvgpr_read_b32 v17, a1
	v_accvgpr_read_b32 v16, a0
	s_lshl_b64 s[10:11], s[8:9], 11
	s_add_u32 s12, s2, s10
	s_addc_u32 s13, s3, s11
	s_lshl_b32 s9, s38, 11
	v_accvgpr_read_b32 v66, a70
	s_add_u32 s40, s16, s9
; __device__ __forceinline__ void phase6(const Params& p, char* smem) {
;     ...
;     LoadBf16 al{H3 + (size_t)m0 * 1024, 1024};
;     gemm_mainloop(acc1, al, (const u16*)(ws + OFF_WT_PG) + (size_t)n0 * 1024, 1024, 1024, smem);
	v_accvgpr_read_b32 v67, a71
	s_addc_u32 s41, s17, 0
	v_lshl_add_u64 v[66:67], s[12:13], 0, v[66:67]
	v_lshl_add_u64 v[76:77], v[66:67], 0, v[170:171]
	v_lshl_add_u64 v[66:67], s[40:41], 0, v[192:193]
	v_lshl_add_u64 v[72:73], v[66:67], 0, v[170:171]
	v_accvgpr_read_b32 v66, a72
	v_accvgpr_read_b32 v67, a73
	v_lshl_add_u64 v[66:67], s[12:13], 0, v[66:67]
	v_lshl_add_u64 v[84:85], v[66:67], 0, v[170:171]
	v_lshl_add_u64 v[66:67], s[40:41], 0, v[194:195]
	v_lshl_add_u64 v[80:81], v[66:67], 0, v[170:171]
	v_accvgpr_read_b32 v66, a74
	v_accvgpr_read_b32 v67, a75
	v_lshl_add_u64 v[66:67], s[12:13], 0, v[66:67]
	v_lshl_add_u64 v[92:93], v[66:67], 0, v[170:171]
	v_lshl_add_u64 v[66:67], s[40:41], 0, v[196:197]
	v_lshl_add_u64 v[88:89], v[66:67], 0, v[170:171]
	v_accvgpr_read_b32 v66, a76
	v_accvgpr_read_b32 v67, a77
	v_lshl_add_u64 v[66:67], s[12:13], 0, v[66:67]
	v_lshl_add_u64 v[100:101], v[66:67], 0, v[170:171]
	v_lshl_add_u64 v[66:67], s[40:41], 0, v[198:199]
	v_lshl_add_u64 v[96:97], v[66:67], 0, v[170:171]
	v_accvgpr_read_b32 v66, a78
	v_accvgpr_read_b32 v67, a79
	v_lshl_add_u64 v[66:67], s[12:13], 0, v[66:67]
	v_lshl_add_u64 v[108:109], v[66:67], 0, v[170:171]
	v_lshl_add_u64 v[66:67], s[40:41], 0, v[200:201]
	v_lshl_add_u64 v[104:105], v[66:67], 0, v[170:171]
	v_accvgpr_read_b32 v66, a80
	v_accvgpr_read_b32 v67, a81
	v_lshl_add_u64 v[66:67], s[12:13], 0, v[66:67]
	v_lshl_add_u64 v[116:117], v[66:67], 0, v[170:171]
	v_lshl_add_u64 v[66:67], s[40:41], 0, v[202:203]
	v_lshl_add_u64 v[112:113], v[66:67], 0, v[170:171]
	v_accvgpr_read_b32 v66, a82
	v_lshl_add_u64 v[64:65], s[12:13], 0, v[146:147]
	v_accvgpr_read_b32 v67, a83
	v_lshl_add_u64 v[68:69], v[64:65], 0, v[170:171]
	v_lshl_add_u64 v[64:65], s[40:41], 0, v[190:191]
	v_lshl_add_u64 v[66:67], s[12:13], 0, v[66:67]
	v_lshl_add_u64 v[122:123], s[40:41], 0, v[204:205]
	v_lshl_add_u64 v[64:65], v[64:65], 0, v[170:171]
	v_lshl_add_u64 v[120:121], v[66:67], 0, v[170:171]
	v_lshl_add_u64 v[124:125], v[122:123], 0, v[170:171]
	s_barrier
	s_barrier
	global_load_dwordx4 v[64:67], v[64:65], off
	s_nop 0
	global_load_dwordx4 v[68:71], v[68:69], off
	s_nop 0
	global_load_dwordx4 v[72:75], v[72:73], off
	s_nop 0
	global_load_dwordx4 v[76:79], v[76:77], off
	s_nop 0
	global_load_dwordx4 v[80:83], v[80:81], off
	s_nop 0
	global_load_dwordx4 v[84:87], v[84:85], off
	s_nop 0
	global_load_dwordx4 v[88:91], v[88:89], off
	s_nop 0
	global_load_dwordx4 v[92:95], v[92:93], off
	s_nop 0
	global_load_dwordx4 v[96:99], v[96:97], off
	s_nop 0
	global_load_dwordx4 v[100:103], v[100:101], off
	s_nop 0
	global_load_dwordx4 v[104:107], v[104:105], off
	s_nop 0
	global_load_dwordx4 v[108:111], v[108:109], off
	s_nop 0
	global_load_dwordx4 v[112:115], v[112:113], off
	s_nop 0
	global_load_dwordx4 v[116:119], v[116:117], off
	s_nop 0
	global_load_dwordx4 v[120:123], v[120:121], off
	s_nop 0
	global_load_dwordx4 v[124:127], v[124:125], off
	v_accvgpr_write_b32 a15, 0
	v_accvgpr_write_b32 a14, 0
	v_accvgpr_write_b32 a13, 0
	v_accvgpr_write_b32 a12, 0
	v_accvgpr_write_b32 a11, 0
	v_accvgpr_write_b32 a10, 0
	v_accvgpr_write_b32 a9, 0
	v_accvgpr_write_b32 a8, 0
	v_lshl_add_u64 v[208:209], v[164:165], 0, s[10:11]
	v_accvgpr_write_b32 a7, 0
	v_accvgpr_write_b32 a6, 0
	v_accvgpr_write_b32 a5, 0
	v_accvgpr_write_b32 a4, 0
	v_accvgpr_write_b32 a3, 0
	v_accvgpr_write_b32 a2, 0
	v_accvgpr_write_b32 a1, 0
	v_accvgpr_write_b32 a0, 0
	v_accvgpr_write_b32 a47, 0
	v_accvgpr_write_b32 a46, 0
	v_accvgpr_write_b32 a45, 0
	v_accvgpr_write_b32 a44, 0
	v_accvgpr_write_b32 a43, 0
	v_accvgpr_write_b32 a42, 0
	v_accvgpr_write_b32 a41, 0
	v_accvgpr_write_b32 a40, 0
	v_accvgpr_write_b32 a39, 0
	v_accvgpr_write_b32 a38, 0
	v_accvgpr_write_b32 a37, 0
	v_accvgpr_write_b32 a36, 0
	v_accvgpr_write_b32 a35, 0
	v_accvgpr_write_b32 a34, 0
	v_accvgpr_write_b32 a33, 0
	v_accvgpr_write_b32 a32, 0
	v_accvgpr_write_b32 a63, 0
	v_accvgpr_write_b32 a62, 0
	v_accvgpr_write_b32 a61, 0
	v_accvgpr_write_b32 a60, 0
	v_accvgpr_write_b32 a59, 0
	v_accvgpr_write_b32 a58, 0
	v_accvgpr_write_b32 a57, 0
	v_accvgpr_write_b32 a56, 0
	v_accvgpr_write_b32 a55, 0
	v_accvgpr_write_b32 a54, 0
	v_accvgpr_write_b32 a53, 0
	v_accvgpr_write_b32 a52, 0
	v_accvgpr_write_b32 a51, 0
	v_accvgpr_write_b32 a50, 0
	v_accvgpr_write_b32 a49, 0
	v_accvgpr_write_b32 a48, 0
	v_accvgpr_write_b32 a31, 0
	v_accvgpr_write_b32 a30, 0
	v_accvgpr_write_b32 a29, 0
	v_accvgpr_write_b32 a28, 0
	v_accvgpr_write_b32 a27, 0
	v_accvgpr_write_b32 a26, 0
	v_accvgpr_write_b32 a25, 0
	v_accvgpr_write_b32 a24, 0
	v_accvgpr_write_b32 a23, 0
	v_accvgpr_write_b32 a22, 0
	v_accvgpr_write_b32 a21, 0
	v_accvgpr_write_b32 a20, 0
	v_accvgpr_write_b32 a19, 0
	v_accvgpr_write_b32 a18, 0
	v_accvgpr_write_b32 a17, 0
	v_accvgpr_write_b32 a16, 0
	s_waitcnt vmcnt(14)
	ds_write_b128 v176, v[68:71]
	ds_write_b128 v177, v[64:67]
	s_waitcnt vmcnt(12)
	ds_write_b128 v176, v[76:79] offset:4352
	ds_write_b128 v178, v[72:75]
	s_waitcnt vmcnt(10)
	ds_write_b128 v176, v[84:87] offset:8704
	ds_write_b128 v179, v[80:83]
	s_waitcnt vmcnt(8)
	ds_write_b128 v176, v[92:95] offset:13056
	ds_write_b128 v210, v[88:91]
	s_waitcnt vmcnt(6)
	ds_write_b128 v176, v[100:103] offset:17408
	ds_write_b128 v211, v[96:99]
	s_waitcnt vmcnt(4)
	ds_write_b128 v176, v[108:111] offset:21760
	ds_write_b128 v212, v[104:107]
	s_waitcnt vmcnt(2)
	ds_write_b128 v176, v[116:119] offset:26112
	ds_write_b128 v213, v[112:115]
	s_waitcnt vmcnt(1)
	ds_write_b128 v176, v[120:123] offset:30464
	s_waitcnt vmcnt(0)
	ds_write_b128 v214, v[124:127]
	s_waitcnt lgkmcnt(0)
	s_barrier
	s_branch .LBB0_1584
